# merge-GEMM epilogue: gate loads pipelined 8 deep with counted vmcnt instead of one serialized round trip per load
# speedup vs baseline: 1.0275x; 1.0275x over previous
; __device__ __forceinline__ float fast_rcp(float x) { return __builtin_amdgcn_rcpf(x); }
; __device__ __forceinline__ u32x4 pack8(f32x4 v0, f32x4 v1) { u32x4 w; w.x = cvt_pk_bf16(v0[0], v0[1]); w.y = cvt_pk_bf16(v0[2], v0[3]); w.z = cvt_pk_bf16(v1[0], v1[1]); w.w = cvt_pk_bf16(v1[2], v1[3]); return w; }
;     __device__ __forceinline__ void operator()(f32x4 (&acc)[2][2][4][2], const Unit& u, int seg, int wr, int wc, int fr, int fq) const {
;         const size_t ga = (size_t)seg * (seg == 1 ? O_DK : O_FK / 2), gb = (seg == 0 ? O_DK : O_FK); const int wave = wr * 4 + wc, lane = fq * 16 + fr;
;         const int row0 = u.pm * BM + wr * 64 + fr; const int colt = u.pn * BM + wc * 32 + 8 * fq;
; #pragma unroll
;         for (int ai = 0; ai < 2; ++ai)
; #pragma unroll
;             for (int m = 0; m < 4; ++m) { const int row = row0 + ai * HALF + m * 16;
; #pragma unroll
;                 for (int bj = 0; bj < 2; ++bj) { const int col = colt + bj * HALF;
;                     const u32x4 aw = *(const u32x4*)(P + gate_frag_off(u.pm, u.pn, wave, ai, m, bj, lane, ga));
;                     f32x4 s0 = {bflo(aw.x), bfhi(aw.x), bflo(aw.y), bfhi(aw.y)}, s1 = {bflo(aw.z), bfhi(aw.z), bflo(aw.w), bfhi(aw.w)};
;                     if (seg != 2) { const u32x4 bw = *(const u32x4*)(P + gate_frag_off(u.pm, u.pn, wave, ai, m, bj, lane, gb));
;                         const f32x4 d0 = {bflo(bw.x), bfhi(bw.x), bflo(bw.y), bfhi(bw.y)}, d1 = {bflo(bw.z), bfhi(bw.z), bflo(bw.w), bfhi(bw.w)};
; #pragma unroll
;                         for (int e = 0; e < 4; ++e) { s0[e] *= fast_rcp(d0[e]); s1[e] *= fast_rcp(d1[e]); } }
;                     acc[ai][bj][m][0] *= s0; acc[ai][bj][m][1] *= s1;
;                     if (seg == 2) *(u32x4*)(Mb + (size_t)row * DM + col) = pack8(acc[ai][bj][m][0], acc[ai][bj][m][1]); }
.LBB0_916:
	v_cndmask_b32_e64 v1, 0, 1, s[34:35]
	v_cmp_ne_u32_e64 s[8:9], 1, v1
	s_lshl_b32 s10, s28, 5
	s_lshl_b32 s11, s30, 3
	s_add_i32 s10, s10, s11
	s_or_b32 s10, s10, s58
	s_lshl_b32 s10, s10, 4
	s_add_i32 s26, s10, s70
	s_ashr_i32 s27, s26, 31
	s_lshl_b64 s[26:27], s[26:27], 10
	s_cmp_eq_u32 s29, 2
	s_cbranch_scc1 .Lm3_seg2
	s_cmp_eq_u32 s29, 1
	s_cselect_b32 s10, 0xa000000, 0
	s_add_u32 s10, s26, s10
	s_addc_u32 s11, s27, 0
	v_lshl_add_u64 v[142:143], v[140:141], 0, s[10:11]
	s_cmp_eq_u32 s29, 0
	s_mov_b32 s17, 0x10000000
	s_cselect_b32 s10, 0xa000000, s17
	s_add_u32 s10, s26, s10
	s_addc_u32 s11, s27, 0
	v_lshl_add_u64 v[144:145], v[140:141], 0, s[10:11]
	s_mov_b64 s[10:11], 0x1000
	global_load_dwordx4 v[162:165], v[142:143], off
	global_load_dwordx4 v[166:169], v[144:145], off
	global_load_dwordx4 v[170:173], v[142:143], off offset:1024
	global_load_dwordx4 v[174:177], v[144:145], off offset:1024
	global_load_dwordx4 v[182:185], v[142:143], off offset:2048
	global_load_dwordx4 v[186:189], v[144:145], off offset:2048
	global_load_dwordx4 v[190:193], v[142:143], off offset:3072
	global_load_dwordx4 v[194:197], v[144:145], off offset:3072
	v_lshl_add_u64 v[142:143], v[142:143], 0, s[10:11]
	v_lshl_add_u64 v[144:145], v[144:145], 0, s[10:11]
	global_load_dwordx4 v[198:201], v[142:143], off
	global_load_dwordx4 v[202:205], v[144:145], off
	global_load_dwordx4 v[206:209], v[142:143], off offset:1024
	global_load_dwordx4 v[210:213], v[144:145], off offset:1024
	global_load_dwordx4 v[226:229], v[142:143], off offset:2048
	global_load_dwordx4 v[232:235], v[144:145], off offset:2048
	global_load_dwordx4 v[236:239], v[142:143], off offset:3072
	global_load_dwordx4 v[240:243], v[144:145], off offset:3072
	v_lshl_add_u64 v[142:143], v[142:143], 0, s[10:11]
	v_lshl_add_u64 v[144:145], v[144:145], 0, s[10:11]
	s_waitcnt vmcnt(14)
	v_lshlrev_b32_e32 v146, 16, v166
	v_and_b32_e32 v147, 0xffff0000, v166
	v_lshlrev_b32_e32 v148, 16, v167
	v_and_b32_e32 v149, 0xffff0000, v167
	v_rcp_f32_e32 v146, v146
	v_rcp_f32_e32 v147, v147
	v_rcp_f32_e32 v148, v148
	v_rcp_f32_e32 v149, v149
	v_lshlrev_b32_e32 v150, 16, v162
	v_and_b32_e32 v151, 0xffff0000, v162
	v_lshlrev_b32_e32 v152, 16, v163
	v_and_b32_e32 v153, 0xffff0000, v163
	v_pk_mul_f32 v[150:151], v[146:147], v[150:151]
	v_pk_mul_f32 v[152:153], v[148:149], v[152:153]
	v_pk_mul_f32 v[120:121], v[120:121], v[150:151]
	v_pk_mul_f32 v[122:123], v[122:123], v[152:153]
	v_lshlrev_b32_e32 v146, 16, v168
	v_and_b32_e32 v147, 0xffff0000, v168
	v_lshlrev_b32_e32 v148, 16, v169
	v_and_b32_e32 v149, 0xffff0000, v169
	v_rcp_f32_e32 v146, v146
	v_rcp_f32_e32 v147, v147
	v_rcp_f32_e32 v148, v148
	v_rcp_f32_e32 v149, v149
	v_lshlrev_b32_e32 v150, 16, v164
	v_and_b32_e32 v151, 0xffff0000, v164
	v_lshlrev_b32_e32 v152, 16, v165
	v_and_b32_e32 v153, 0xffff0000, v165
	v_pk_mul_f32 v[150:151], v[146:147], v[150:151]
	v_pk_mul_f32 v[152:153], v[148:149], v[152:153]
	v_pk_mul_f32 v[116:117], v[116:117], v[150:151]
	v_pk_mul_f32 v[118:119], v[118:119], v[152:153]
	global_load_dwordx4 v[162:165], v[142:143], off
	global_load_dwordx4 v[166:169], v[144:145], off
	s_waitcnt vmcnt(14)
	v_lshlrev_b32_e32 v146, 16, v174
	v_and_b32_e32 v147, 0xffff0000, v174
	v_lshlrev_b32_e32 v148, 16, v175
	v_and_b32_e32 v149, 0xffff0000, v175
	v_rcp_f32_e32 v146, v146
	v_rcp_f32_e32 v147, v147
	v_rcp_f32_e32 v148, v148
	v_rcp_f32_e32 v149, v149
	v_lshlrev_b32_e32 v150, 16, v170
	v_and_b32_e32 v151, 0xffff0000, v170
	v_lshlrev_b32_e32 v152, 16, v171
	v_and_b32_e32 v153, 0xffff0000, v171
	v_pk_mul_f32 v[150:151], v[146:147], v[150:151]
	v_pk_mul_f32 v[152:153], v[148:149], v[152:153]
	v_pk_mul_f32 v[88:89], v[88:89], v[150:151]
	v_pk_mul_f32 v[90:91], v[90:91], v[152:153]
	v_lshlrev_b32_e32 v146, 16, v176
	v_and_b32_e32 v147, 0xffff0000, v176
	v_lshlrev_b32_e32 v148, 16, v177
	v_and_b32_e32 v149, 0xffff0000, v177
	v_rcp_f32_e32 v146, v146
	v_rcp_f32_e32 v147, v147
	v_rcp_f32_e32 v148, v148
	v_rcp_f32_e32 v149, v149
	v_lshlrev_b32_e32 v150, 16, v172
	v_and_b32_e32 v151, 0xffff0000, v172
	v_lshlrev_b32_e32 v152, 16, v173
	v_and_b32_e32 v153, 0xffff0000, v173
	v_pk_mul_f32 v[150:151], v[146:147], v[150:151]
	v_pk_mul_f32 v[152:153], v[148:149], v[152:153]
	v_pk_mul_f32 v[84:85], v[84:85], v[150:151]
	v_pk_mul_f32 v[86:87], v[86:87], v[152:153]
	global_load_dwordx4 v[170:173], v[142:143], off offset:1024
	global_load_dwordx4 v[174:177], v[144:145], off offset:1024
	s_waitcnt vmcnt(14)
	v_lshlrev_b32_e32 v146, 16, v186
	v_and_b32_e32 v147, 0xffff0000, v186
	v_lshlrev_b32_e32 v148, 16, v187
	v_and_b32_e32 v149, 0xffff0000, v187
	v_rcp_f32_e32 v146, v146
	v_rcp_f32_e32 v147, v147
	v_rcp_f32_e32 v148, v148
	v_rcp_f32_e32 v149, v149
	v_lshlrev_b32_e32 v150, 16, v182
	v_and_b32_e32 v151, 0xffff0000, v182
	v_lshlrev_b32_e32 v152, 16, v183
	v_and_b32_e32 v153, 0xffff0000, v183
	v_pk_mul_f32 v[150:151], v[146:147], v[150:151]
	v_pk_mul_f32 v[152:153], v[148:149], v[152:153]
	v_pk_mul_f32 v[112:113], v[112:113], v[150:151]
	v_pk_mul_f32 v[114:115], v[114:115], v[152:153]
	v_lshlrev_b32_e32 v146, 16, v188
	v_and_b32_e32 v147, 0xffff0000, v188
	v_lshlrev_b32_e32 v148, 16, v189
	v_and_b32_e32 v149, 0xffff0000, v189
	v_rcp_f32_e32 v146, v146
	v_rcp_f32_e32 v147, v147
	v_rcp_f32_e32 v148, v148
	v_rcp_f32_e32 v149, v149
	v_lshlrev_b32_e32 v150, 16, v184
	v_and_b32_e32 v151, 0xffff0000, v184
	v_lshlrev_b32_e32 v152, 16, v185
	v_and_b32_e32 v153, 0xffff0000, v185
	v_pk_mul_f32 v[150:151], v[146:147], v[150:151]
	v_pk_mul_f32 v[152:153], v[148:149], v[152:153]
	v_pk_mul_f32 v[108:109], v[108:109], v[150:151]
	v_pk_mul_f32 v[110:111], v[110:111], v[152:153]
	global_load_dwordx4 v[182:185], v[142:143], off offset:2048
	global_load_dwordx4 v[186:189], v[144:145], off offset:2048
	s_waitcnt vmcnt(14)
; __device__ __forceinline__ float fast_rcp(float x) { return __builtin_amdgcn_rcpf(x); }
;     __device__ __forceinline__ void operator()(f32x4 (&acc)[2][2][4][2], const Unit& u, int seg, int wr, int wc, int fr, int fq) const {
;     ...
;                 for (int bj = 0; bj < 2; ++bj) { const int col = colt + bj * HALF;
;                     const u32x4 aw = *(const u32x4*)(P + gate_frag_off(u.pm, u.pn, wave, ai, m, bj, lane, ga));
;                     f32x4 s0 = {bflo(aw.x), bfhi(aw.x), bflo(aw.y), bfhi(aw.y)}, s1 = {bflo(aw.z), bfhi(aw.z), bflo(aw.w), bfhi(aw.w)};
;                     if (seg != 2) { const u32x4 bw = *(const u32x4*)(P + gate_frag_off(u.pm, u.pn, wave, ai, m, bj, lane, gb));
;                         const f32x4 d0 = {bflo(bw.x), bfhi(bw.x), bflo(bw.y), bfhi(bw.y)}, d1 = {bflo(bw.z), bfhi(bw.z), bflo(bw.w), bfhi(bw.w)};
; #pragma unroll
;                         for (int e = 0; e < 4; ++e) { s0[e] *= fast_rcp(d0[e]); s1[e] *= fast_rcp(d1[e]); } }
;                     acc[ai][bj][m][0] *= s0; acc[ai][bj][m][1] *= s1;
	v_lshlrev_b32_e32 v146, 16, v194
	v_and_b32_e32 v147, 0xffff0000, v194
	v_lshlrev_b32_e32 v148, 16, v195
	v_and_b32_e32 v149, 0xffff0000, v195
	v_rcp_f32_e32 v146, v146
	v_rcp_f32_e32 v147, v147
	v_rcp_f32_e32 v148, v148
	v_rcp_f32_e32 v149, v149
	v_lshlrev_b32_e32 v150, 16, v190
	v_and_b32_e32 v151, 0xffff0000, v190
	v_lshlrev_b32_e32 v152, 16, v191
	v_and_b32_e32 v153, 0xffff0000, v191
	v_pk_mul_f32 v[150:151], v[146:147], v[150:151]
	v_pk_mul_f32 v[152:153], v[148:149], v[152:153]
	v_pk_mul_f32 v[80:81], v[80:81], v[150:151]
	v_pk_mul_f32 v[82:83], v[82:83], v[152:153]
	v_lshlrev_b32_e32 v146, 16, v196
	v_and_b32_e32 v147, 0xffff0000, v196
	v_lshlrev_b32_e32 v148, 16, v197
	v_and_b32_e32 v149, 0xffff0000, v197
	v_rcp_f32_e32 v146, v146
	v_rcp_f32_e32 v147, v147
	v_rcp_f32_e32 v148, v148
	v_rcp_f32_e32 v149, v149
	v_lshlrev_b32_e32 v150, 16, v192
	v_and_b32_e32 v151, 0xffff0000, v192
	v_lshlrev_b32_e32 v152, 16, v193
	v_and_b32_e32 v153, 0xffff0000, v193
	v_pk_mul_f32 v[150:151], v[146:147], v[150:151]
	v_pk_mul_f32 v[152:153], v[148:149], v[152:153]
	v_pk_mul_f32 v[76:77], v[76:77], v[150:151]
	v_pk_mul_f32 v[78:79], v[78:79], v[152:153]
	global_load_dwordx4 v[190:193], v[142:143], off offset:3072
	global_load_dwordx4 v[194:197], v[144:145], off offset:3072
	v_lshl_add_u64 v[142:143], v[142:143], 0, s[10:11]
	v_lshl_add_u64 v[144:145], v[144:145], 0, s[10:11]
	s_waitcnt vmcnt(14)
	v_lshlrev_b32_e32 v146, 16, v202
	v_and_b32_e32 v147, 0xffff0000, v202
	v_lshlrev_b32_e32 v148, 16, v203
	v_and_b32_e32 v149, 0xffff0000, v203
	v_rcp_f32_e32 v146, v146
	v_rcp_f32_e32 v147, v147
	v_rcp_f32_e32 v148, v148
	v_rcp_f32_e32 v149, v149
	v_lshlrev_b32_e32 v150, 16, v198
	v_and_b32_e32 v151, 0xffff0000, v198
	v_lshlrev_b32_e32 v152, 16, v199
	v_and_b32_e32 v153, 0xffff0000, v199
	v_pk_mul_f32 v[150:151], v[146:147], v[150:151]
	v_pk_mul_f32 v[152:153], v[148:149], v[152:153]
	v_pk_mul_f32 v[104:105], v[104:105], v[150:151]
	v_pk_mul_f32 v[106:107], v[106:107], v[152:153]
	v_lshlrev_b32_e32 v146, 16, v204
	v_and_b32_e32 v147, 0xffff0000, v204
	v_lshlrev_b32_e32 v148, 16, v205
	v_and_b32_e32 v149, 0xffff0000, v205
	v_rcp_f32_e32 v146, v146
	v_rcp_f32_e32 v147, v147
	v_rcp_f32_e32 v148, v148
	v_rcp_f32_e32 v149, v149
	v_lshlrev_b32_e32 v150, 16, v200
	v_and_b32_e32 v151, 0xffff0000, v200
	v_lshlrev_b32_e32 v152, 16, v201
	v_and_b32_e32 v153, 0xffff0000, v201
	v_pk_mul_f32 v[150:151], v[146:147], v[150:151]
	v_pk_mul_f32 v[152:153], v[148:149], v[152:153]
	v_pk_mul_f32 v[100:101], v[100:101], v[150:151]
	v_pk_mul_f32 v[102:103], v[102:103], v[152:153]
	global_load_dwordx4 v[198:201], v[142:143], off
	global_load_dwordx4 v[202:205], v[144:145], off
	s_waitcnt vmcnt(14)
	v_lshlrev_b32_e32 v146, 16, v210
	v_and_b32_e32 v147, 0xffff0000, v210
	v_lshlrev_b32_e32 v148, 16, v211
	v_and_b32_e32 v149, 0xffff0000, v211
	v_rcp_f32_e32 v146, v146
	v_rcp_f32_e32 v147, v147
	v_rcp_f32_e32 v148, v148
	v_rcp_f32_e32 v149, v149
	v_lshlrev_b32_e32 v150, 16, v206
	v_and_b32_e32 v151, 0xffff0000, v206
	v_lshlrev_b32_e32 v152, 16, v207
	v_and_b32_e32 v153, 0xffff0000, v207
	v_pk_mul_f32 v[150:151], v[146:147], v[150:151]
	v_pk_mul_f32 v[152:153], v[148:149], v[152:153]
	v_pk_mul_f32 v[72:73], v[72:73], v[150:151]
	v_pk_mul_f32 v[74:75], v[74:75], v[152:153]
	v_lshlrev_b32_e32 v146, 16, v212
	v_and_b32_e32 v147, 0xffff0000, v212
	v_lshlrev_b32_e32 v148, 16, v213
	v_and_b32_e32 v149, 0xffff0000, v213
	v_rcp_f32_e32 v146, v146
	v_rcp_f32_e32 v147, v147
	v_rcp_f32_e32 v148, v148
	v_rcp_f32_e32 v149, v149
	v_lshlrev_b32_e32 v150, 16, v208
	v_and_b32_e32 v151, 0xffff0000, v208
	v_lshlrev_b32_e32 v152, 16, v209
	v_and_b32_e32 v153, 0xffff0000, v209
	v_pk_mul_f32 v[150:151], v[146:147], v[150:151]
	v_pk_mul_f32 v[152:153], v[148:149], v[152:153]
	v_pk_mul_f32 v[68:69], v[68:69], v[150:151]
	v_pk_mul_f32 v[70:71], v[70:71], v[152:153]
	global_load_dwordx4 v[206:209], v[142:143], off offset:1024
	global_load_dwordx4 v[210:213], v[144:145], off offset:1024
	s_waitcnt vmcnt(14)
	v_lshlrev_b32_e32 v146, 16, v232
	v_and_b32_e32 v147, 0xffff0000, v232
	v_lshlrev_b32_e32 v148, 16, v233
	v_and_b32_e32 v149, 0xffff0000, v233
	v_rcp_f32_e32 v146, v146
	v_rcp_f32_e32 v147, v147
	v_rcp_f32_e32 v148, v148
	v_rcp_f32_e32 v149, v149
	v_lshlrev_b32_e32 v150, 16, v226
	v_and_b32_e32 v151, 0xffff0000, v226
	v_lshlrev_b32_e32 v152, 16, v227
	v_and_b32_e32 v153, 0xffff0000, v227
	v_pk_mul_f32 v[150:151], v[146:147], v[150:151]
	v_pk_mul_f32 v[152:153], v[148:149], v[152:153]
	v_pk_mul_f32 v[96:97], v[96:97], v[150:151]
	v_pk_mul_f32 v[98:99], v[98:99], v[152:153]
	v_lshlrev_b32_e32 v146, 16, v234
	v_and_b32_e32 v147, 0xffff0000, v234
	v_lshlrev_b32_e32 v148, 16, v235
	v_and_b32_e32 v149, 0xffff0000, v235
	v_rcp_f32_e32 v146, v146
	v_rcp_f32_e32 v147, v147
	v_rcp_f32_e32 v148, v148
	v_rcp_f32_e32 v149, v149
	v_lshlrev_b32_e32 v150, 16, v228
	v_and_b32_e32 v151, 0xffff0000, v228
	v_lshlrev_b32_e32 v152, 16, v229
	v_and_b32_e32 v153, 0xffff0000, v229
	v_pk_mul_f32 v[150:151], v[146:147], v[150:151]
	v_pk_mul_f32 v[152:153], v[148:149], v[152:153]
	v_pk_mul_f32 v[92:93], v[92:93], v[150:151]
	v_pk_mul_f32 v[94:95], v[94:95], v[152:153]
	global_load_dwordx4 v[226:229], v[142:143], off offset:2048
	global_load_dwordx4 v[232:235], v[144:145], off offset:2048
	s_waitcnt vmcnt(14)
; __device__ __forceinline__ float fast_rcp(float x) { return __builtin_amdgcn_rcpf(x); }
;     __device__ __forceinline__ void operator()(f32x4 (&acc)[2][2][4][2], const Unit& u, int seg, int wr, int wc, int fr, int fq) const {
;     ...
;                 for (int bj = 0; bj < 2; ++bj) { const int col = colt + bj * HALF;
;                     const u32x4 aw = *(const u32x4*)(P + gate_frag_off(u.pm, u.pn, wave, ai, m, bj, lane, ga));
;                     f32x4 s0 = {bflo(aw.x), bfhi(aw.x), bflo(aw.y), bfhi(aw.y)}, s1 = {bflo(aw.z), bfhi(aw.z), bflo(aw.w), bfhi(aw.w)};
;                     if (seg != 2) { const u32x4 bw = *(const u32x4*)(P + gate_frag_off(u.pm, u.pn, wave, ai, m, bj, lane, gb));
;                         const f32x4 d0 = {bflo(bw.x), bfhi(bw.x), bflo(bw.y), bfhi(bw.y)}, d1 = {bflo(bw.z), bfhi(bw.z), bflo(bw.w), bfhi(bw.w)};
; #pragma unroll
;                         for (int e = 0; e < 4; ++e) { s0[e] *= fast_rcp(d0[e]); s1[e] *= fast_rcp(d1[e]); } }
;                     acc[ai][bj][m][0] *= s0; acc[ai][bj][m][1] *= s1;
	v_lshlrev_b32_e32 v146, 16, v240
	v_and_b32_e32 v147, 0xffff0000, v240
	v_lshlrev_b32_e32 v148, 16, v241
	v_and_b32_e32 v149, 0xffff0000, v241
	v_rcp_f32_e32 v146, v146
	v_rcp_f32_e32 v147, v147
	v_rcp_f32_e32 v148, v148
	v_rcp_f32_e32 v149, v149
	v_lshlrev_b32_e32 v150, 16, v236
	v_and_b32_e32 v151, 0xffff0000, v236
	v_lshlrev_b32_e32 v152, 16, v237
	v_and_b32_e32 v153, 0xffff0000, v237
	v_pk_mul_f32 v[150:151], v[146:147], v[150:151]
	v_pk_mul_f32 v[152:153], v[148:149], v[152:153]
	v_pk_mul_f32 v[64:65], v[64:65], v[150:151]
	v_pk_mul_f32 v[66:67], v[66:67], v[152:153]
	v_lshlrev_b32_e32 v146, 16, v242
	v_and_b32_e32 v147, 0xffff0000, v242
	v_lshlrev_b32_e32 v148, 16, v243
	v_and_b32_e32 v149, 0xffff0000, v243
	v_rcp_f32_e32 v146, v146
	v_rcp_f32_e32 v147, v147
	v_rcp_f32_e32 v148, v148
	v_rcp_f32_e32 v149, v149
	v_lshlrev_b32_e32 v150, 16, v238
	v_and_b32_e32 v151, 0xffff0000, v238
	v_lshlrev_b32_e32 v152, 16, v239
	v_and_b32_e32 v153, 0xffff0000, v239
	v_pk_mul_f32 v[150:151], v[146:147], v[150:151]
	v_pk_mul_f32 v[152:153], v[148:149], v[152:153]
	v_pk_mul_f32 v[60:61], v[60:61], v[150:151]
	v_pk_mul_f32 v[62:63], v[62:63], v[152:153]
	global_load_dwordx4 v[236:239], v[142:143], off offset:3072
	global_load_dwordx4 v[240:243], v[144:145], off offset:3072
	s_waitcnt vmcnt(14)
	v_lshlrev_b32_e32 v146, 16, v166
	v_and_b32_e32 v147, 0xffff0000, v166
	v_lshlrev_b32_e32 v148, 16, v167
	v_and_b32_e32 v149, 0xffff0000, v167
	v_rcp_f32_e32 v146, v146
	v_rcp_f32_e32 v147, v147
	v_rcp_f32_e32 v148, v148
	v_rcp_f32_e32 v149, v149
	v_lshlrev_b32_e32 v150, 16, v162
	v_and_b32_e32 v151, 0xffff0000, v162
	v_lshlrev_b32_e32 v152, 16, v163
	v_and_b32_e32 v153, 0xffff0000, v163
	v_pk_mul_f32 v[150:151], v[146:147], v[150:151]
	v_pk_mul_f32 v[152:153], v[148:149], v[152:153]
	v_pk_mul_f32 v[56:57], v[56:57], v[150:151]
	v_pk_mul_f32 v[58:59], v[58:59], v[152:153]
	v_lshlrev_b32_e32 v146, 16, v168
	v_and_b32_e32 v147, 0xffff0000, v168
	v_lshlrev_b32_e32 v148, 16, v169
	v_and_b32_e32 v149, 0xffff0000, v169
	v_rcp_f32_e32 v146, v146
	v_rcp_f32_e32 v147, v147
	v_rcp_f32_e32 v148, v148
	v_rcp_f32_e32 v149, v149
	v_lshlrev_b32_e32 v150, 16, v164
	v_and_b32_e32 v151, 0xffff0000, v164
	v_lshlrev_b32_e32 v152, 16, v165
	v_and_b32_e32 v153, 0xffff0000, v165
	v_pk_mul_f32 v[150:151], v[146:147], v[150:151]
	v_pk_mul_f32 v[152:153], v[148:149], v[152:153]
	v_pk_mul_f32 v[52:53], v[52:53], v[150:151]
	v_pk_mul_f32 v[54:55], v[54:55], v[152:153]
	s_waitcnt vmcnt(12)
	v_lshlrev_b32_e32 v146, 16, v174
	v_and_b32_e32 v147, 0xffff0000, v174
	v_lshlrev_b32_e32 v148, 16, v175
	v_and_b32_e32 v149, 0xffff0000, v175
	v_rcp_f32_e32 v146, v146
	v_rcp_f32_e32 v147, v147
	v_rcp_f32_e32 v148, v148
	v_rcp_f32_e32 v149, v149
	v_lshlrev_b32_e32 v150, 16, v170
	v_and_b32_e32 v151, 0xffff0000, v170
	v_lshlrev_b32_e32 v152, 16, v171
	v_and_b32_e32 v153, 0xffff0000, v171
	v_pk_mul_f32 v[150:151], v[146:147], v[150:151]
	v_pk_mul_f32 v[152:153], v[148:149], v[152:153]
	v_pk_mul_f32 v[24:25], v[24:25], v[150:151]
	v_pk_mul_f32 v[26:27], v[26:27], v[152:153]
	v_lshlrev_b32_e32 v146, 16, v176
	v_and_b32_e32 v147, 0xffff0000, v176
	v_lshlrev_b32_e32 v148, 16, v177
	v_and_b32_e32 v149, 0xffff0000, v177
	v_rcp_f32_e32 v146, v146
	v_rcp_f32_e32 v147, v147
	v_rcp_f32_e32 v148, v148
	v_rcp_f32_e32 v149, v149
	v_lshlrev_b32_e32 v150, 16, v172
	v_and_b32_e32 v151, 0xffff0000, v172
	v_lshlrev_b32_e32 v152, 16, v173
	v_and_b32_e32 v153, 0xffff0000, v173
	v_pk_mul_f32 v[150:151], v[146:147], v[150:151]
	v_pk_mul_f32 v[152:153], v[148:149], v[152:153]
	v_pk_mul_f32 v[20:21], v[20:21], v[150:151]
	v_pk_mul_f32 v[22:23], v[22:23], v[152:153]
	s_waitcnt vmcnt(10)
	v_lshlrev_b32_e32 v146, 16, v186
	v_and_b32_e32 v147, 0xffff0000, v186
	v_lshlrev_b32_e32 v148, 16, v187
	v_and_b32_e32 v149, 0xffff0000, v187
	v_rcp_f32_e32 v146, v146
	v_rcp_f32_e32 v147, v147
	v_rcp_f32_e32 v148, v148
	v_rcp_f32_e32 v149, v149
	v_lshlrev_b32_e32 v150, 16, v182
	v_and_b32_e32 v151, 0xffff0000, v182
	v_lshlrev_b32_e32 v152, 16, v183
	v_and_b32_e32 v153, 0xffff0000, v183
	v_pk_mul_f32 v[150:151], v[146:147], v[150:151]
	v_pk_mul_f32 v[152:153], v[148:149], v[152:153]
	v_pk_mul_f32 v[48:49], v[48:49], v[150:151]
	v_pk_mul_f32 v[50:51], v[50:51], v[152:153]
	v_lshlrev_b32_e32 v146, 16, v188
	v_and_b32_e32 v147, 0xffff0000, v188
	v_lshlrev_b32_e32 v148, 16, v189
	v_and_b32_e32 v149, 0xffff0000, v189
	v_rcp_f32_e32 v146, v146
	v_rcp_f32_e32 v147, v147
	v_rcp_f32_e32 v148, v148
	v_rcp_f32_e32 v149, v149
	v_lshlrev_b32_e32 v150, 16, v184
	v_and_b32_e32 v151, 0xffff0000, v184
	v_lshlrev_b32_e32 v152, 16, v185
	v_and_b32_e32 v153, 0xffff0000, v185
	v_pk_mul_f32 v[150:151], v[146:147], v[150:151]
	v_pk_mul_f32 v[152:153], v[148:149], v[152:153]
	v_pk_mul_f32 v[44:45], v[44:45], v[150:151]
	v_pk_mul_f32 v[46:47], v[46:47], v[152:153]
	s_waitcnt vmcnt(8)
	v_lshlrev_b32_e32 v146, 16, v194
	v_and_b32_e32 v147, 0xffff0000, v194
	v_lshlrev_b32_e32 v148, 16, v195
	v_and_b32_e32 v149, 0xffff0000, v195
	v_rcp_f32_e32 v146, v146
	v_rcp_f32_e32 v147, v147
	v_rcp_f32_e32 v148, v148
	v_rcp_f32_e32 v149, v149
	v_lshlrev_b32_e32 v150, 16, v190
	v_and_b32_e32 v151, 0xffff0000, v190
	v_lshlrev_b32_e32 v152, 16, v191
	v_and_b32_e32 v153, 0xffff0000, v191
	v_pk_mul_f32 v[150:151], v[146:147], v[150:151]
	v_pk_mul_f32 v[152:153], v[148:149], v[152:153]
	v_pk_mul_f32 v[16:17], v[16:17], v[150:151]
	v_pk_mul_f32 v[18:19], v[18:19], v[152:153]
	v_lshlrev_b32_e32 v146, 16, v196
	v_and_b32_e32 v147, 0xffff0000, v196
	v_lshlrev_b32_e32 v148, 16, v197
	v_and_b32_e32 v149, 0xffff0000, v197
	v_rcp_f32_e32 v146, v146
	v_rcp_f32_e32 v147, v147
	v_rcp_f32_e32 v148, v148
	v_rcp_f32_e32 v149, v149
	v_lshlrev_b32_e32 v150, 16, v192
	v_and_b32_e32 v151, 0xffff0000, v192
	v_lshlrev_b32_e32 v152, 16, v193
	v_and_b32_e32 v153, 0xffff0000, v193
	v_pk_mul_f32 v[150:151], v[146:147], v[150:151]
	v_pk_mul_f32 v[152:153], v[148:149], v[152:153]
	v_pk_mul_f32 v[12:13], v[12:13], v[150:151]
	v_pk_mul_f32 v[14:15], v[14:15], v[152:153]
	s_waitcnt vmcnt(6)
; __device__ __forceinline__ float fast_rcp(float x) { return __builtin_amdgcn_rcpf(x); }
;     __device__ __forceinline__ void operator()(f32x4 (&acc)[2][2][4][2], const Unit& u, int seg, int wr, int wc, int fr, int fq) const {
;     ...
;                 for (int bj = 0; bj < 2; ++bj) { const int col = colt + bj * HALF;
;                     const u32x4 aw = *(const u32x4*)(P + gate_frag_off(u.pm, u.pn, wave, ai, m, bj, lane, ga));
;                     f32x4 s0 = {bflo(aw.x), bfhi(aw.x), bflo(aw.y), bfhi(aw.y)}, s1 = {bflo(aw.z), bfhi(aw.z), bflo(aw.w), bfhi(aw.w)};
;                     if (seg != 2) { const u32x4 bw = *(const u32x4*)(P + gate_frag_off(u.pm, u.pn, wave, ai, m, bj, lane, gb));
;                         const f32x4 d0 = {bflo(bw.x), bfhi(bw.x), bflo(bw.y), bfhi(bw.y)}, d1 = {bflo(bw.z), bfhi(bw.z), bflo(bw.w), bfhi(bw.w)};
; #pragma unroll
;                         for (int e = 0; e < 4; ++e) { s0[e] *= fast_rcp(d0[e]); s1[e] *= fast_rcp(d1[e]); } }
;                     acc[ai][bj][m][0] *= s0; acc[ai][bj][m][1] *= s1;
	v_lshlrev_b32_e32 v146, 16, v202
	v_and_b32_e32 v147, 0xffff0000, v202
	v_lshlrev_b32_e32 v148, 16, v203
	v_and_b32_e32 v149, 0xffff0000, v203
	v_rcp_f32_e32 v146, v146
	v_rcp_f32_e32 v147, v147
	v_rcp_f32_e32 v148, v148
	v_rcp_f32_e32 v149, v149
	v_lshlrev_b32_e32 v150, 16, v198
	v_and_b32_e32 v151, 0xffff0000, v198
	v_lshlrev_b32_e32 v152, 16, v199
	v_and_b32_e32 v153, 0xffff0000, v199
	v_pk_mul_f32 v[150:151], v[146:147], v[150:151]
	v_pk_mul_f32 v[152:153], v[148:149], v[152:153]
	v_pk_mul_f32 v[40:41], v[40:41], v[150:151]
	v_pk_mul_f32 v[42:43], v[42:43], v[152:153]
	v_lshlrev_b32_e32 v146, 16, v204
	v_and_b32_e32 v147, 0xffff0000, v204
	v_lshlrev_b32_e32 v148, 16, v205
	v_and_b32_e32 v149, 0xffff0000, v205
	v_rcp_f32_e32 v146, v146
	v_rcp_f32_e32 v147, v147
	v_rcp_f32_e32 v148, v148
	v_rcp_f32_e32 v149, v149
	v_lshlrev_b32_e32 v150, 16, v200
	v_and_b32_e32 v151, 0xffff0000, v200
	v_lshlrev_b32_e32 v152, 16, v201
	v_and_b32_e32 v153, 0xffff0000, v201
	v_pk_mul_f32 v[150:151], v[146:147], v[150:151]
	v_pk_mul_f32 v[152:153], v[148:149], v[152:153]
	v_pk_mul_f32 v[36:37], v[36:37], v[150:151]
	v_pk_mul_f32 v[38:39], v[38:39], v[152:153]
	s_waitcnt vmcnt(4)
	v_lshlrev_b32_e32 v146, 16, v210
	v_and_b32_e32 v147, 0xffff0000, v210
	v_lshlrev_b32_e32 v148, 16, v211
	v_and_b32_e32 v149, 0xffff0000, v211
	v_rcp_f32_e32 v146, v146
	v_rcp_f32_e32 v147, v147
	v_rcp_f32_e32 v148, v148
	v_rcp_f32_e32 v149, v149
	v_lshlrev_b32_e32 v150, 16, v206
	v_and_b32_e32 v151, 0xffff0000, v206
	v_lshlrev_b32_e32 v152, 16, v207
	v_and_b32_e32 v153, 0xffff0000, v207
	v_pk_mul_f32 v[150:151], v[146:147], v[150:151]
	v_pk_mul_f32 v[152:153], v[148:149], v[152:153]
	v_pk_mul_f32 v[8:9], v[8:9], v[150:151]
	v_pk_mul_f32 v[10:11], v[10:11], v[152:153]
	v_lshlrev_b32_e32 v146, 16, v212
	v_and_b32_e32 v147, 0xffff0000, v212
	v_lshlrev_b32_e32 v148, 16, v213
	v_and_b32_e32 v149, 0xffff0000, v213
	v_rcp_f32_e32 v146, v146
	v_rcp_f32_e32 v147, v147
	v_rcp_f32_e32 v148, v148
	v_rcp_f32_e32 v149, v149
	v_lshlrev_b32_e32 v150, 16, v208
	v_and_b32_e32 v151, 0xffff0000, v208
	v_lshlrev_b32_e32 v152, 16, v209
	v_and_b32_e32 v153, 0xffff0000, v209
	v_pk_mul_f32 v[150:151], v[146:147], v[150:151]
	v_pk_mul_f32 v[152:153], v[148:149], v[152:153]
	v_pk_mul_f32 v[4:5], v[4:5], v[150:151]
	v_pk_mul_f32 v[6:7], v[6:7], v[152:153]
	s_waitcnt vmcnt(2)
	v_lshlrev_b32_e32 v146, 16, v232
	v_and_b32_e32 v147, 0xffff0000, v232
	v_lshlrev_b32_e32 v148, 16, v233
	v_and_b32_e32 v149, 0xffff0000, v233
	v_rcp_f32_e32 v146, v146
	v_rcp_f32_e32 v147, v147
	v_rcp_f32_e32 v148, v148
	v_rcp_f32_e32 v149, v149
	v_lshlrev_b32_e32 v150, 16, v226
	v_and_b32_e32 v151, 0xffff0000, v226
	v_lshlrev_b32_e32 v152, 16, v227
	v_and_b32_e32 v153, 0xffff0000, v227
	v_pk_mul_f32 v[150:151], v[146:147], v[150:151]
	v_pk_mul_f32 v[152:153], v[148:149], v[152:153]
	v_pk_mul_f32 v[32:33], v[32:33], v[150:151]
	v_pk_mul_f32 v[34:35], v[34:35], v[152:153]
	v_lshlrev_b32_e32 v146, 16, v234
	v_and_b32_e32 v147, 0xffff0000, v234
	v_lshlrev_b32_e32 v148, 16, v235
	v_and_b32_e32 v149, 0xffff0000, v235
	v_rcp_f32_e32 v146, v146
	v_rcp_f32_e32 v147, v147
	v_rcp_f32_e32 v148, v148
	v_rcp_f32_e32 v149, v149
	v_lshlrev_b32_e32 v150, 16, v228
	v_and_b32_e32 v151, 0xffff0000, v228
	v_lshlrev_b32_e32 v152, 16, v229
	v_and_b32_e32 v153, 0xffff0000, v229
	v_pk_mul_f32 v[150:151], v[146:147], v[150:151]
	v_pk_mul_f32 v[152:153], v[148:149], v[152:153]
	v_pk_mul_f32 v[28:29], v[28:29], v[150:151]
	v_pk_mul_f32 v[30:31], v[30:31], v[152:153]
	s_waitcnt vmcnt(0)
	v_lshlrev_b32_e32 v146, 16, v240
	v_and_b32_e32 v147, 0xffff0000, v240
	v_lshlrev_b32_e32 v148, 16, v241
	v_and_b32_e32 v149, 0xffff0000, v241
	v_rcp_f32_e32 v146, v146
	v_rcp_f32_e32 v147, v147
	v_rcp_f32_e32 v148, v148
	v_rcp_f32_e32 v149, v149
	v_lshlrev_b32_e32 v150, 16, v236
	v_and_b32_e32 v151, 0xffff0000, v236
	v_lshlrev_b32_e32 v152, 16, v237
	v_and_b32_e32 v153, 0xffff0000, v237
	v_pk_mul_f32 v[150:151], v[146:147], v[150:151]
	v_pk_mul_f32 v[152:153], v[148:149], v[152:153]
	v_pk_mul_f32 v[124:125], v[124:125], v[150:151]
	v_pk_mul_f32 v[126:127], v[126:127], v[152:153]
	v_lshlrev_b32_e32 v146, 16, v242
	v_and_b32_e32 v147, 0xffff0000, v242
	v_lshlrev_b32_e32 v148, 16, v243
	v_and_b32_e32 v149, 0xffff0000, v243
	v_rcp_f32_e32 v146, v146
	v_rcp_f32_e32 v147, v147
	v_rcp_f32_e32 v148, v148
	v_rcp_f32_e32 v149, v149
	v_lshlrev_b32_e32 v150, 16, v238
	v_and_b32_e32 v151, 0xffff0000, v238
	v_lshlrev_b32_e32 v152, 16, v239
	v_and_b32_e32 v153, 0xffff0000, v239
	v_pk_mul_f32 v[150:151], v[146:147], v[150:151]
	v_pk_mul_f32 v[152:153], v[148:149], v[152:153]
	v_pk_mul_f32 v[128:129], v[128:129], v[150:151]
	v_pk_mul_f32 v[130:131], v[130:131], v[152:153]
	s_branch .Lm3_done
; __device__ __forceinline__ float fast_rcp(float x) { return __builtin_amdgcn_rcpf(x); }
; __device__ __forceinline__ u32x4 pack8(f32x4 v0, f32x4 v1) { u32x4 w; w.x = cvt_pk_bf16(v0[0], v0[1]); w.y = cvt_pk_bf16(v0[2], v0[3]); w.z = cvt_pk_bf16(v1[0], v1[1]); w.w = cvt_pk_bf16(v1[2], v1[3]); return w; }
;     __device__ __forceinline__ void operator()(f32x4 (&acc)[2][2][4][2], const Unit& u, int seg, int wr, int wc, int fr, int fq) const {
;     ...
;             for (int m = 0; m < 4; ++m) { const int row = row0 + ai * HALF + m * 16;
; #pragma unroll
;                 for (int bj = 0; bj < 2; ++bj) { const int col = colt + bj * HALF;
;                     const u32x4 aw = *(const u32x4*)(P + gate_frag_off(u.pm, u.pn, wave, ai, m, bj, lane, ga));
;                     f32x4 s0 = {bflo(aw.x), bfhi(aw.x), bflo(aw.y), bfhi(aw.y)}, s1 = {bflo(aw.z), bfhi(aw.z), bflo(aw.w), bfhi(aw.w)};
;                     if (seg != 2) { const u32x4 bw = *(const u32x4*)(P + gate_frag_off(u.pm, u.pn, wave, ai, m, bj, lane, gb));
;                         const f32x4 d0 = {bflo(bw.x), bfhi(bw.x), bflo(bw.y), bfhi(bw.y)}, d1 = {bflo(bw.z), bfhi(bw.z), bflo(bw.w), bfhi(bw.w)};
; #pragma unroll
;                         for (int e = 0; e < 4; ++e) { s0[e] *= fast_rcp(d0[e]); s1[e] *= fast_rcp(d1[e]); } }
;                     acc[ai][bj][m][0] *= s0; acc[ai][bj][m][1] *= s1;
;                     if (seg == 2) *(u32x4*)(Mb + (size_t)row * DM + col) = pack8(acc[ai][bj][m][0], acc[ai][bj][m][1]); }
.Lm3_seg2:
	s_add_u32 s10, s26, 0x10000000
	s_addc_u32 s11, s27, 0
	v_lshl_add_u64 v[142:143], v[140:141], 0, s[10:11]
	s_mov_b64 s[10:11], 0x1000
	global_load_dwordx4 v[162:165], v[142:143], off
	global_load_dwordx4 v[166:169], v[142:143], off offset:1024
	global_load_dwordx4 v[170:173], v[142:143], off offset:2048
	global_load_dwordx4 v[174:177], v[142:143], off offset:3072
	v_lshl_add_u64 v[142:143], v[142:143], 0, s[10:11]
	global_load_dwordx4 v[182:185], v[142:143], off
	global_load_dwordx4 v[186:189], v[142:143], off offset:1024
	global_load_dwordx4 v[190:193], v[142:143], off offset:2048
	global_load_dwordx4 v[194:197], v[142:143], off offset:3072
	v_lshl_add_u64 v[142:143], v[142:143], 0, s[10:11]
	global_load_dwordx4 v[198:201], v[142:143], off
	global_load_dwordx4 v[202:205], v[142:143], off offset:1024
	global_load_dwordx4 v[206:209], v[142:143], off offset:2048
	global_load_dwordx4 v[210:213], v[142:143], off offset:3072
	v_lshl_add_u64 v[142:143], v[142:143], 0, s[10:11]
	global_load_dwordx4 v[226:229], v[142:143], off
	global_load_dwordx4 v[232:235], v[142:143], off offset:1024
	global_load_dwordx4 v[236:239], v[142:143], off offset:2048
	global_load_dwordx4 v[240:243], v[142:143], off offset:3072
	v_lshl_add_u32 v144, s28, 8, v156
	v_lshl_or_b32 v2, s30, 8, v158
	v_lshlrev_b32_e32 v144, 11, v144
	v_lshl_add_u32 v144, v2, 1, v144
	s_waitcnt vmcnt(15)
	v_lshlrev_b32_e32 v146, 16, v162
	v_and_b32_e32 v147, 0xffff0000, v162
	v_lshlrev_b32_e32 v148, 16, v163
	v_and_b32_e32 v149, 0xffff0000, v163
	v_lshlrev_b32_e32 v150, 16, v164
	v_and_b32_e32 v151, 0xffff0000, v164
	v_lshlrev_b32_e32 v152, 16, v165
	v_and_b32_e32 v153, 0xffff0000, v165
	v_pk_mul_f32 v[120:121], v[120:121], v[146:147]
	v_pk_mul_f32 v[122:123], v[122:123], v[148:149]
	v_pk_mul_f32 v[116:117], v[116:117], v[150:151]
	v_pk_mul_f32 v[118:119], v[118:119], v[152:153]
	v_cvt_pk_bf16_f32 v162, v120, v121
	v_cvt_pk_bf16_f32 v163, v122, v123
	v_cvt_pk_bf16_f32 v164, v116, v117
	v_cvt_pk_bf16_f32 v165, v118, v119
	s_mov_b64 s[10:11], s[4:5]
	global_store_dwordx4 v144, v[162:165], s[10:11]
	s_waitcnt vmcnt(15)
	v_lshlrev_b32_e32 v146, 16, v166
	v_and_b32_e32 v147, 0xffff0000, v166
	v_lshlrev_b32_e32 v148, 16, v167
	v_and_b32_e32 v149, 0xffff0000, v167
	v_lshlrev_b32_e32 v150, 16, v168
	v_and_b32_e32 v151, 0xffff0000, v168
	v_lshlrev_b32_e32 v152, 16, v169
	v_and_b32_e32 v153, 0xffff0000, v169
	v_pk_mul_f32 v[88:89], v[88:89], v[146:147]
	v_pk_mul_f32 v[90:91], v[90:91], v[148:149]
	v_pk_mul_f32 v[84:85], v[84:85], v[150:151]
	v_pk_mul_f32 v[86:87], v[86:87], v[152:153]
	v_cvt_pk_bf16_f32 v166, v88, v89
	v_cvt_pk_bf16_f32 v167, v90, v91
	v_cvt_pk_bf16_f32 v168, v84, v85
	v_cvt_pk_bf16_f32 v169, v86, v87
	global_store_dwordx4 v144, v[166:169], s[10:11] offset:256
	s_waitcnt vmcnt(15)
	v_lshlrev_b32_e32 v146, 16, v170
	v_and_b32_e32 v147, 0xffff0000, v170
	v_lshlrev_b32_e32 v148, 16, v171
	v_and_b32_e32 v149, 0xffff0000, v171
	v_lshlrev_b32_e32 v150, 16, v172
	v_and_b32_e32 v151, 0xffff0000, v172
	v_lshlrev_b32_e32 v152, 16, v173
	v_and_b32_e32 v153, 0xffff0000, v173
	v_pk_mul_f32 v[112:113], v[112:113], v[146:147]
	v_pk_mul_f32 v[114:115], v[114:115], v[148:149]
	v_pk_mul_f32 v[108:109], v[108:109], v[150:151]
	v_pk_mul_f32 v[110:111], v[110:111], v[152:153]
	v_cvt_pk_bf16_f32 v170, v112, v113
	v_cvt_pk_bf16_f32 v171, v114, v115
	v_cvt_pk_bf16_f32 v172, v108, v109
	v_cvt_pk_bf16_f32 v173, v110, v111
	s_add_u32 s10, s4, 0x8000
	s_addc_u32 s11, s5, 0
	global_store_dwordx4 v144, v[170:173], s[10:11]
	s_waitcnt vmcnt(15)
	v_lshlrev_b32_e32 v146, 16, v174
	v_and_b32_e32 v147, 0xffff0000, v174
	v_lshlrev_b32_e32 v148, 16, v175
	v_and_b32_e32 v149, 0xffff0000, v175
	v_lshlrev_b32_e32 v150, 16, v176
	v_and_b32_e32 v151, 0xffff0000, v176
	v_lshlrev_b32_e32 v152, 16, v177
	v_and_b32_e32 v153, 0xffff0000, v177
	v_pk_mul_f32 v[80:81], v[80:81], v[146:147]
	v_pk_mul_f32 v[82:83], v[82:83], v[148:149]
	v_pk_mul_f32 v[76:77], v[76:77], v[150:151]
	v_pk_mul_f32 v[78:79], v[78:79], v[152:153]
	v_cvt_pk_bf16_f32 v174, v80, v81
	v_cvt_pk_bf16_f32 v175, v82, v83
	v_cvt_pk_bf16_f32 v176, v76, v77
	v_cvt_pk_bf16_f32 v177, v78, v79
	global_store_dwordx4 v144, v[174:177], s[10:11] offset:256
	s_waitcnt vmcnt(15)
	v_lshlrev_b32_e32 v146, 16, v182
	v_and_b32_e32 v147, 0xffff0000, v182
	v_lshlrev_b32_e32 v148, 16, v183
	v_and_b32_e32 v149, 0xffff0000, v183
	v_lshlrev_b32_e32 v150, 16, v184
	v_and_b32_e32 v151, 0xffff0000, v184
	v_lshlrev_b32_e32 v152, 16, v185
	v_and_b32_e32 v153, 0xffff0000, v185
	v_pk_mul_f32 v[104:105], v[104:105], v[146:147]
	v_pk_mul_f32 v[106:107], v[106:107], v[148:149]
	v_pk_mul_f32 v[100:101], v[100:101], v[150:151]
	v_pk_mul_f32 v[102:103], v[102:103], v[152:153]
	v_cvt_pk_bf16_f32 v182, v104, v105
	v_cvt_pk_bf16_f32 v183, v106, v107
	v_cvt_pk_bf16_f32 v184, v100, v101
	v_cvt_pk_bf16_f32 v185, v102, v103
	s_add_u32 s10, s4, 0x10000
	s_addc_u32 s11, s5, 0
	global_store_dwordx4 v144, v[182:185], s[10:11]
	s_waitcnt vmcnt(15)
	v_lshlrev_b32_e32 v146, 16, v186
	v_and_b32_e32 v147, 0xffff0000, v186
	v_lshlrev_b32_e32 v148, 16, v187
	v_and_b32_e32 v149, 0xffff0000, v187
	v_lshlrev_b32_e32 v150, 16, v188
	v_and_b32_e32 v151, 0xffff0000, v188
	v_lshlrev_b32_e32 v152, 16, v189
	v_and_b32_e32 v153, 0xffff0000, v189
	v_pk_mul_f32 v[72:73], v[72:73], v[146:147]
	v_pk_mul_f32 v[74:75], v[74:75], v[148:149]
	v_pk_mul_f32 v[68:69], v[68:69], v[150:151]
	v_pk_mul_f32 v[70:71], v[70:71], v[152:153]
	v_cvt_pk_bf16_f32 v186, v72, v73
	v_cvt_pk_bf16_f32 v187, v74, v75
	v_cvt_pk_bf16_f32 v188, v68, v69
	v_cvt_pk_bf16_f32 v189, v70, v71
	global_store_dwordx4 v144, v[186:189], s[10:11] offset:256
	s_waitcnt vmcnt(15)
; __device__ __forceinline__ float fast_rcp(float x) { return __builtin_amdgcn_rcpf(x); }
; __device__ __forceinline__ u32x4 pack8(f32x4 v0, f32x4 v1) { u32x4 w; w.x = cvt_pk_bf16(v0[0], v0[1]); w.y = cvt_pk_bf16(v0[2], v0[3]); w.z = cvt_pk_bf16(v1[0], v1[1]); w.w = cvt_pk_bf16(v1[2], v1[3]); return w; }
;     __device__ __forceinline__ void operator()(f32x4 (&acc)[2][2][4][2], const Unit& u, int seg, int wr, int wc, int fr, int fq) const {
;     ...
;             for (int m = 0; m < 4; ++m) { const int row = row0 + ai * HALF + m * 16;
; #pragma unroll
;                 for (int bj = 0; bj < 2; ++bj) { const int col = colt + bj * HALF;
;                     const u32x4 aw = *(const u32x4*)(P + gate_frag_off(u.pm, u.pn, wave, ai, m, bj, lane, ga));
;                     f32x4 s0 = {bflo(aw.x), bfhi(aw.x), bflo(aw.y), bfhi(aw.y)}, s1 = {bflo(aw.z), bfhi(aw.z), bflo(aw.w), bfhi(aw.w)};
;                     if (seg != 2) { const u32x4 bw = *(const u32x4*)(P + gate_frag_off(u.pm, u.pn, wave, ai, m, bj, lane, gb));
;                         const f32x4 d0 = {bflo(bw.x), bfhi(bw.x), bflo(bw.y), bfhi(bw.y)}, d1 = {bflo(bw.z), bfhi(bw.z), bflo(bw.w), bfhi(bw.w)};
; #pragma unroll
;                         for (int e = 0; e < 4; ++e) { s0[e] *= fast_rcp(d0[e]); s1[e] *= fast_rcp(d1[e]); } }
;                     acc[ai][bj][m][0] *= s0; acc[ai][bj][m][1] *= s1;
;                     if (seg == 2) *(u32x4*)(Mb + (size_t)row * DM + col) = pack8(acc[ai][bj][m][0], acc[ai][bj][m][1]); }
	v_lshlrev_b32_e32 v146, 16, v190
	v_and_b32_e32 v147, 0xffff0000, v190
	v_lshlrev_b32_e32 v148, 16, v191
	v_and_b32_e32 v149, 0xffff0000, v191
	v_lshlrev_b32_e32 v150, 16, v192
	v_and_b32_e32 v151, 0xffff0000, v192
	v_lshlrev_b32_e32 v152, 16, v193
	v_and_b32_e32 v153, 0xffff0000, v193
	v_pk_mul_f32 v[96:97], v[96:97], v[146:147]
	v_pk_mul_f32 v[98:99], v[98:99], v[148:149]
	v_pk_mul_f32 v[92:93], v[92:93], v[150:151]
	v_pk_mul_f32 v[94:95], v[94:95], v[152:153]
	v_cvt_pk_bf16_f32 v190, v96, v97
	v_cvt_pk_bf16_f32 v191, v98, v99
	v_cvt_pk_bf16_f32 v192, v92, v93
	v_cvt_pk_bf16_f32 v193, v94, v95
	s_add_u32 s10, s4, 0x18000
	s_addc_u32 s11, s5, 0
	global_store_dwordx4 v144, v[190:193], s[10:11]
	s_waitcnt vmcnt(15)
	v_lshlrev_b32_e32 v146, 16, v194
	v_and_b32_e32 v147, 0xffff0000, v194
	v_lshlrev_b32_e32 v148, 16, v195
	v_and_b32_e32 v149, 0xffff0000, v195
	v_lshlrev_b32_e32 v150, 16, v196
	v_and_b32_e32 v151, 0xffff0000, v196
	v_lshlrev_b32_e32 v152, 16, v197
	v_and_b32_e32 v153, 0xffff0000, v197
	v_pk_mul_f32 v[64:65], v[64:65], v[146:147]
	v_pk_mul_f32 v[66:67], v[66:67], v[148:149]
	v_pk_mul_f32 v[60:61], v[60:61], v[150:151]
	v_pk_mul_f32 v[62:63], v[62:63], v[152:153]
	v_cvt_pk_bf16_f32 v194, v64, v65
	v_cvt_pk_bf16_f32 v195, v66, v67
	v_cvt_pk_bf16_f32 v196, v60, v61
	v_cvt_pk_bf16_f32 v197, v62, v63
	global_store_dwordx4 v144, v[194:197], s[10:11] offset:256
	s_waitcnt vmcnt(15)
	v_lshlrev_b32_e32 v146, 16, v198
	v_and_b32_e32 v147, 0xffff0000, v198
	v_lshlrev_b32_e32 v148, 16, v199
	v_and_b32_e32 v149, 0xffff0000, v199
	v_lshlrev_b32_e32 v150, 16, v200
	v_and_b32_e32 v151, 0xffff0000, v200
	v_lshlrev_b32_e32 v152, 16, v201
	v_and_b32_e32 v153, 0xffff0000, v201
	v_pk_mul_f32 v[56:57], v[56:57], v[146:147]
	v_pk_mul_f32 v[58:59], v[58:59], v[148:149]
	v_pk_mul_f32 v[52:53], v[52:53], v[150:151]
	v_pk_mul_f32 v[54:55], v[54:55], v[152:153]
	v_cvt_pk_bf16_f32 v198, v56, v57
	v_cvt_pk_bf16_f32 v199, v58, v59
	v_cvt_pk_bf16_f32 v200, v52, v53
	v_cvt_pk_bf16_f32 v201, v54, v55
	s_add_u32 s10, s4, 0x40000
	s_addc_u32 s11, s5, 0
	global_store_dwordx4 v144, v[198:201], s[10:11]
	s_waitcnt vmcnt(15)
	v_lshlrev_b32_e32 v146, 16, v202
	v_and_b32_e32 v147, 0xffff0000, v202
	v_lshlrev_b32_e32 v148, 16, v203
	v_and_b32_e32 v149, 0xffff0000, v203
	v_lshlrev_b32_e32 v150, 16, v204
	v_and_b32_e32 v151, 0xffff0000, v204
	v_lshlrev_b32_e32 v152, 16, v205
	v_and_b32_e32 v153, 0xffff0000, v205
	v_pk_mul_f32 v[24:25], v[24:25], v[146:147]
	v_pk_mul_f32 v[26:27], v[26:27], v[148:149]
	v_pk_mul_f32 v[20:21], v[20:21], v[150:151]
	v_pk_mul_f32 v[22:23], v[22:23], v[152:153]
	v_cvt_pk_bf16_f32 v202, v24, v25
	v_cvt_pk_bf16_f32 v203, v26, v27
	v_cvt_pk_bf16_f32 v204, v20, v21
	v_cvt_pk_bf16_f32 v205, v22, v23
	global_store_dwordx4 v144, v[202:205], s[10:11] offset:256
	s_waitcnt vmcnt(15)
	v_lshlrev_b32_e32 v146, 16, v206
	v_and_b32_e32 v147, 0xffff0000, v206
	v_lshlrev_b32_e32 v148, 16, v207
	v_and_b32_e32 v149, 0xffff0000, v207
	v_lshlrev_b32_e32 v150, 16, v208
	v_and_b32_e32 v151, 0xffff0000, v208
	v_lshlrev_b32_e32 v152, 16, v209
	v_and_b32_e32 v153, 0xffff0000, v209
	v_pk_mul_f32 v[48:49], v[48:49], v[146:147]
	v_pk_mul_f32 v[50:51], v[50:51], v[148:149]
	v_pk_mul_f32 v[44:45], v[44:45], v[150:151]
	v_pk_mul_f32 v[46:47], v[46:47], v[152:153]
	v_cvt_pk_bf16_f32 v206, v48, v49
	v_cvt_pk_bf16_f32 v207, v50, v51
	v_cvt_pk_bf16_f32 v208, v44, v45
	v_cvt_pk_bf16_f32 v209, v46, v47
	s_add_u32 s10, s4, 0x48000
	s_addc_u32 s11, s5, 0
	global_store_dwordx4 v144, v[206:209], s[10:11]
	s_waitcnt vmcnt(15)
	v_lshlrev_b32_e32 v146, 16, v210
	v_and_b32_e32 v147, 0xffff0000, v210
	v_lshlrev_b32_e32 v148, 16, v211
	v_and_b32_e32 v149, 0xffff0000, v211
	v_lshlrev_b32_e32 v150, 16, v212
	v_and_b32_e32 v151, 0xffff0000, v212
	v_lshlrev_b32_e32 v152, 16, v213
	v_and_b32_e32 v153, 0xffff0000, v213
	v_pk_mul_f32 v[16:17], v[16:17], v[146:147]
	v_pk_mul_f32 v[18:19], v[18:19], v[148:149]
	v_pk_mul_f32 v[12:13], v[12:13], v[150:151]
	v_pk_mul_f32 v[14:15], v[14:15], v[152:153]
	v_cvt_pk_bf16_f32 v210, v16, v17
	v_cvt_pk_bf16_f32 v211, v18, v19
	v_cvt_pk_bf16_f32 v212, v12, v13
	v_cvt_pk_bf16_f32 v213, v14, v15
	global_store_dwordx4 v144, v[210:213], s[10:11] offset:256
	s_waitcnt vmcnt(15)
	v_lshlrev_b32_e32 v146, 16, v226
	v_and_b32_e32 v147, 0xffff0000, v226
	v_lshlrev_b32_e32 v148, 16, v227
	v_and_b32_e32 v149, 0xffff0000, v227
	v_lshlrev_b32_e32 v150, 16, v228
	v_and_b32_e32 v151, 0xffff0000, v228
	v_lshlrev_b32_e32 v152, 16, v229
	v_and_b32_e32 v153, 0xffff0000, v229
	v_pk_mul_f32 v[40:41], v[40:41], v[146:147]
	v_pk_mul_f32 v[42:43], v[42:43], v[148:149]
	v_pk_mul_f32 v[36:37], v[36:37], v[150:151]
	v_pk_mul_f32 v[38:39], v[38:39], v[152:153]
	v_cvt_pk_bf16_f32 v226, v40, v41
	v_cvt_pk_bf16_f32 v227, v42, v43
	v_cvt_pk_bf16_f32 v228, v36, v37
	v_cvt_pk_bf16_f32 v229, v38, v39
	s_add_u32 s10, s4, 0x50000
	s_addc_u32 s11, s5, 0
	global_store_dwordx4 v144, v[226:229], s[10:11]
	s_waitcnt vmcnt(15)
	v_lshlrev_b32_e32 v146, 16, v232
	v_and_b32_e32 v147, 0xffff0000, v232
	v_lshlrev_b32_e32 v148, 16, v233
	v_and_b32_e32 v149, 0xffff0000, v233
	v_lshlrev_b32_e32 v150, 16, v234
	v_and_b32_e32 v151, 0xffff0000, v234
	v_lshlrev_b32_e32 v152, 16, v235
	v_and_b32_e32 v153, 0xffff0000, v235
	v_pk_mul_f32 v[8:9], v[8:9], v[146:147]
	v_pk_mul_f32 v[10:11], v[10:11], v[148:149]
	v_pk_mul_f32 v[4:5], v[4:5], v[150:151]
	v_pk_mul_f32 v[6:7], v[6:7], v[152:153]
	v_cvt_pk_bf16_f32 v232, v8, v9
	v_cvt_pk_bf16_f32 v233, v10, v11
	v_cvt_pk_bf16_f32 v234, v4, v5
	v_cvt_pk_bf16_f32 v235, v6, v7
	global_store_dwordx4 v144, v[232:235], s[10:11] offset:256
	s_waitcnt vmcnt(15)
	v_lshlrev_b32_e32 v146, 16, v236
	v_and_b32_e32 v147, 0xffff0000, v236
	v_lshlrev_b32_e32 v148, 16, v237
	v_and_b32_e32 v149, 0xffff0000, v237
	v_lshlrev_b32_e32 v150, 16, v238
	v_and_b32_e32 v151, 0xffff0000, v238
	v_lshlrev_b32_e32 v152, 16, v239
	v_and_b32_e32 v153, 0xffff0000, v239
	v_pk_mul_f32 v[32:33], v[32:33], v[146:147]
	v_pk_mul_f32 v[34:35], v[34:35], v[148:149]
	v_pk_mul_f32 v[28:29], v[28:29], v[150:151]
	v_pk_mul_f32 v[30:31], v[30:31], v[152:153]
	v_cvt_pk_bf16_f32 v236, v32, v33
	v_cvt_pk_bf16_f32 v237, v34, v35
	v_cvt_pk_bf16_f32 v238, v28, v29
	v_cvt_pk_bf16_f32 v239, v30, v31
	s_add_u32 s10, s4, 0x58000
	s_addc_u32 s11, s5, 0
	global_store_dwordx4 v144, v[236:239], s[10:11]
	s_waitcnt vmcnt(15)
	v_lshlrev_b32_e32 v146, 16, v240
	v_and_b32_e32 v147, 0xffff0000, v240
	v_lshlrev_b32_e32 v148, 16, v241
	v_and_b32_e32 v149, 0xffff0000, v241
	v_lshlrev_b32_e32 v150, 16, v242
	v_and_b32_e32 v151, 0xffff0000, v242
	v_lshlrev_b32_e32 v152, 16, v243
	v_and_b32_e32 v153, 0xffff0000, v243
	v_pk_mul_f32 v[124:125], v[124:125], v[146:147]
	v_pk_mul_f32 v[126:127], v[126:127], v[148:149]
	v_pk_mul_f32 v[128:129], v[128:129], v[150:151]
	v_pk_mul_f32 v[130:131], v[130:131], v[152:153]
	v_cvt_pk_bf16_f32 v240, v124, v125
	v_cvt_pk_bf16_f32 v241, v126, v127
	v_cvt_pk_bf16_f32 v242, v128, v129
	v_cvt_pk_bf16_f32 v243, v130, v131
	global_store_dwordx4 v144, v[240:243], s[10:11] offset:256
; #define PG8_BAR __builtin_amdgcn_s_barrier()
; #define PG8_BAR __builtin_amdgcn_s_barrier()
; template <class Epi, class Sched>
; __device__ __forceinline__ void gemm_phase3(LAS unsigned char* lds, const Gemm3 g, const Sched& S, const Epi& E) {
;     ...
;         E(acc, cur, seg, wr, wc, fr, fq);
;         if (!has_next) break;
;         if (seg == 2) {
; #pragma unroll
;         for (int a = 0; a < 2; ++a)
; #pragma unroll
;             for (int b = 0; b < 2; ++b)
; #pragma unroll
;                 for (int m = 0; m < 4; ++m)
; #pragma unroll
;                     for (int n = 0; n < 2; ++n) acc[a][b][m][n] = (f32x4){0.f, 0.f, 0.f, 0.f};
;         ++ui; }
;         cur = nxt; cA = nA; cB = nB; seg = nseg; nt = g.nt(seg); voffA[0] = nvoffA[0]; voffA[1] = nvoffA[1]; hstepA = nhstepA;
;         if (wr == 1) PG8_BAR;
.Lm3_done:
.LBB0_980:
	s_and_b64 vcc, exec, s[6:7]
	s_mov_b64 s[6:7], -1
	s_cbranch_vccnz .LBB0_895
	s_and_b64 vcc, exec, s[8:9]
	s_cbranch_vccnz .LBB0_983
	v_mov_b32_e32 v2, v0
	v_mov_b32_e32 v3, v0
	v_mov_b32_e32 v1, v0
	v_mov_b64_e32 v[6:7], v[2:3]
	v_mov_b64_e32 v[10:11], v[2:3]
	v_mov_b64_e32 v[14:15], v[2:3]
	v_mov_b64_e32 v[18:19], v[2:3]
	v_mov_b64_e32 v[22:23], v[2:3]
	v_mov_b64_e32 v[26:27], v[2:3]
	v_mov_b64_e32 v[30:31], v[2:3]
	v_mov_b64_e32 v[34:35], v[2:3]
	v_mov_b64_e32 v[38:39], v[2:3]
	v_mov_b64_e32 v[42:43], v[2:3]
	v_mov_b64_e32 v[46:47], v[2:3]
	v_mov_b64_e32 v[50:51], v[2:3]
	v_mov_b64_e32 v[54:55], v[2:3]
	v_mov_b64_e32 v[58:59], v[2:3]
	v_mov_b64_e32 v[62:63], v[2:3]
	v_mov_b64_e32 v[66:67], v[2:3]
	v_mov_b64_e32 v[70:71], v[2:3]
	v_mov_b64_e32 v[74:75], v[2:3]
	v_mov_b64_e32 v[78:79], v[2:3]
	v_mov_b64_e32 v[82:83], v[2:3]
	v_mov_b64_e32 v[86:87], v[2:3]
	v_mov_b64_e32 v[90:91], v[2:3]
	v_mov_b64_e32 v[94:95], v[2:3]
	v_mov_b64_e32 v[98:99], v[2:3]
	v_mov_b64_e32 v[102:103], v[2:3]
	v_mov_b64_e32 v[106:107], v[2:3]
	v_mov_b64_e32 v[110:111], v[2:3]
	v_mov_b64_e32 v[114:115], v[2:3]
	v_mov_b64_e32 v[118:119], v[2:3]
	v_mov_b64_e32 v[122:123], v[2:3]
	v_mov_b64_e32 v[126:127], v[2:3]
	v_mov_b64_e32 v[130:131], v[2:3]
	s_add_i32 s74, s74, 1
	v_mov_b64_e32 v[4:5], v[0:1]
	v_mov_b64_e32 v[8:9], v[0:1]
	v_mov_b64_e32 v[12:13], v[0:1]
	v_mov_b64_e32 v[16:17], v[0:1]
	v_mov_b64_e32 v[20:21], v[0:1]
	v_mov_b64_e32 v[24:25], v[0:1]
	v_mov_b64_e32 v[28:29], v[0:1]
	v_mov_b64_e32 v[32:33], v[0:1]
	v_mov_b64_e32 v[36:37], v[0:1]
	v_mov_b64_e32 v[40:41], v[0:1]
	v_mov_b64_e32 v[44:45], v[0:1]
	v_mov_b64_e32 v[48:49], v[0:1]
	v_mov_b64_e32 v[52:53], v[0:1]
	v_mov_b64_e32 v[56:57], v[0:1]
	v_mov_b64_e32 v[60:61], v[0:1]
	v_mov_b64_e32 v[64:65], v[0:1]
	v_mov_b64_e32 v[68:69], v[0:1]
	v_mov_b64_e32 v[72:73], v[0:1]
	v_mov_b64_e32 v[76:77], v[0:1]
	v_mov_b64_e32 v[80:81], v[0:1]
	v_mov_b64_e32 v[84:85], v[0:1]
	v_mov_b64_e32 v[88:89], v[0:1]
	v_mov_b64_e32 v[92:93], v[0:1]
	v_mov_b64_e32 v[96:97], v[0:1]
	v_mov_b64_e32 v[100:101], v[0:1]
	v_mov_b64_e32 v[104:105], v[0:1]
	v_mov_b64_e32 v[108:109], v[0:1]
	v_mov_b64_e32 v[112:113], v[0:1]
	v_mov_b64_e32 v[116:117], v[0:1]
	v_mov_b64_e32 v[120:121], v[0:1]
	v_mov_b64_e32 v[124:125], v[0:1]
	v_mov_b64_e32 v[128:129], v[0:1]

.LBB0_1241:
	v_lshl_add_u32 v144, s42, 8, v1
	v_lshl_or_b32 v142, s43, 8, v149
	v_ashrrev_i32_e32 v145, 31, v144
	v_ashrrev_i32_e32 v143, 31, v142
	v_lshlrev_b64 v[146:147], 12, v[144:145]
	v_lshl_add_u64 v[152:153], s[8:9], 0, v[146:147]
	v_lshlrev_b64 v[146:147], 2, v[142:143]
	v_lshl_add_u64 v[142:143], v[152:153], 0, v[146:147]
	flat_load_dwordx4 v[152:155], v[142:143]
	flat_load_dwordx4 v[156:159], v[142:143] offset:16
	s_mov_b64 s[14:15], 0x80000
	s_waitcnt vmcnt(0) lgkmcnt(0)
	v_pk_add_f32 v[128:129], v[128:129], v[154:155]
	v_pk_add_f32 v[126:127], v[126:127], v[152:153]
	v_pk_add_f32 v[124:125], v[124:125], v[158:159]
	v_pk_add_f32 v[122:123], v[122:123], v[156:157]
	flat_store_dwordx4 v[142:143], v[126:129]
	flat_store_dwordx4 v[142:143], v[122:125] offset:16
	flat_load_dwordx4 v[122:125], v[142:143] offset:512
	s_nop 0
	flat_load_dwordx4 v[126:129], v[142:143] offset:528
	s_waitcnt vmcnt(0) lgkmcnt(0)
	v_pk_add_f32 v[120:121], v[120:121], v[124:125]
	v_pk_add_f32 v[116:117], v[116:117], v[128:129]
	v_pk_add_f32 v[114:115], v[114:115], v[126:127]
	flat_store_dwordx4 v[142:143], v[114:117] offset:528
	v_pk_add_f32 v[118:119], v[118:119], v[122:123]
	flat_store_dwordx4 v[142:143], v[118:121] offset:512
	v_or_b32_e32 v114, 16, v144
	v_ashrrev_i32_e32 v115, 31, v114
	v_lshlrev_b64 v[114:115], 12, v[114:115]
	v_lshl_add_u64 v[114:115], s[8:9], 0, v[114:115]
	v_lshl_add_u64 v[122:123], v[114:115], 0, v[146:147]
	flat_load_dwordx4 v[114:117], v[122:123]
	flat_load_dwordx4 v[118:121], v[122:123] offset:16
	s_waitcnt vmcnt(0) lgkmcnt(0)
	v_pk_add_f32 v[112:113], v[112:113], v[116:117]
	v_pk_add_f32 v[110:111], v[110:111], v[114:115]
	v_pk_add_f32 v[108:109], v[108:109], v[120:121]
	v_pk_add_f32 v[106:107], v[106:107], v[118:119]
	flat_store_dwordx4 v[122:123], v[110:113]
	flat_store_dwordx4 v[122:123], v[106:109] offset:16
	flat_load_dwordx4 v[106:109], v[122:123] offset:512
	s_nop 0
	flat_load_dwordx4 v[110:113], v[122:123] offset:528
	s_waitcnt vmcnt(0) lgkmcnt(0)
	v_pk_add_f32 v[104:105], v[104:105], v[108:109]
	v_pk_add_f32 v[100:101], v[100:101], v[112:113]
	v_pk_add_f32 v[98:99], v[98:99], v[110:111]
	flat_store_dwordx4 v[122:123], v[98:101] offset:528
	v_pk_add_f32 v[102:103], v[102:103], v[106:107]
	flat_store_dwordx4 v[122:123], v[102:105] offset:512
	v_or_b32_e32 v98, 32, v144
	v_ashrrev_i32_e32 v99, 31, v98
	v_lshlrev_b64 v[98:99], 12, v[98:99]
	v_lshl_add_u64 v[98:99], s[8:9], 0, v[98:99]
	v_lshl_add_u64 v[106:107], v[98:99], 0, v[146:147]
	flat_load_dwordx4 v[98:101], v[106:107]
	flat_load_dwordx4 v[102:105], v[106:107] offset:16
	s_waitcnt vmcnt(0) lgkmcnt(0)
	v_pk_add_f32 v[96:97], v[96:97], v[100:101]
	v_pk_add_f32 v[94:95], v[94:95], v[98:99]
	v_pk_add_f32 v[92:93], v[92:93], v[104:105]
	v_pk_add_f32 v[90:91], v[90:91], v[102:103]
	flat_store_dwordx4 v[106:107], v[94:97]
	flat_store_dwordx4 v[106:107], v[90:93] offset:16
	flat_load_dwordx4 v[90:93], v[106:107] offset:512
	s_nop 0
	flat_load_dwordx4 v[94:97], v[106:107] offset:528
	s_waitcnt vmcnt(0) lgkmcnt(0)
	v_pk_add_f32 v[88:89], v[88:89], v[92:93]
	v_pk_add_f32 v[84:85], v[84:85], v[96:97]
	v_pk_add_f32 v[82:83], v[82:83], v[94:95]
	flat_store_dwordx4 v[106:107], v[82:85] offset:528
	v_pk_add_f32 v[86:87], v[86:87], v[90:91]
	flat_store_dwordx4 v[106:107], v[86:89] offset:512
	v_or_b32_e32 v82, 48, v144
	v_ashrrev_i32_e32 v83, 31, v82
	v_lshlrev_b64 v[82:83], 12, v[82:83]
	v_lshl_add_u64 v[82:83], s[8:9], 0, v[82:83]
	v_lshl_add_u64 v[90:91], v[82:83], 0, v[146:147]
	flat_load_dwordx4 v[82:85], v[90:91]
	flat_load_dwordx4 v[86:89], v[90:91] offset:16
	s_waitcnt vmcnt(0) lgkmcnt(0)
	v_pk_add_f32 v[80:81], v[80:81], v[84:85]
	v_pk_add_f32 v[78:79], v[78:79], v[82:83]
	v_pk_add_f32 v[76:77], v[76:77], v[88:89]
	v_pk_add_f32 v[74:75], v[74:75], v[86:87]
	flat_store_dwordx4 v[90:91], v[78:81]
	flat_store_dwordx4 v[90:91], v[74:77] offset:16
	flat_load_dwordx4 v[74:77], v[90:91] offset:512
	s_nop 0
	flat_load_dwordx4 v[78:81], v[90:91] offset:528
	s_waitcnt vmcnt(0) lgkmcnt(0)
	v_pk_add_f32 v[72:73], v[72:73], v[76:77]
	v_pk_add_f32 v[70:71], v[70:71], v[74:75]
	v_pk_add_f32 v[68:69], v[68:69], v[80:81]
	v_pk_add_f32 v[66:67], v[66:67], v[78:79]
	v_lshl_add_u64 v[74:75], v[142:143], 0, s[14:15]
	s_mov_b32 s14, 0x80000
	flat_store_dwordx4 v[90:91], v[70:73] offset:512
	flat_store_dwordx4 v[90:91], v[66:69] offset:528
	v_add_co_u32_e32 v76, vcc, s14, v142
	s_mov_b64 s[14:15], 0x90000
	s_nop 0
	v_addc_co_u32_e32 v77, vcc, 0, v143, vcc
	flat_load_dwordx4 v[66:69], v[76:77]
	flat_load_dwordx4 v[70:73], v[74:75] offset:16
	s_waitcnt vmcnt(0) lgkmcnt(0)
	v_pk_add_f32 v[64:65], v[64:65], v[68:69]
	v_pk_add_f32 v[62:63], v[62:63], v[66:67]
	v_pk_add_f32 v[60:61], v[60:61], v[72:73]
	v_pk_add_f32 v[58:59], v[58:59], v[70:71]
	flat_store_dwordx4 v[76:77], v[62:65]
	flat_store_dwordx4 v[74:75], v[58:61] offset:16
	flat_load_dwordx4 v[58:61], v[74:75] offset:512
	s_nop 0
	flat_load_dwordx4 v[62:65], v[74:75] offset:528
	s_waitcnt vmcnt(0) lgkmcnt(0)
	v_pk_add_f32 v[54:55], v[54:55], v[58:59]
	v_lshl_add_u64 v[58:59], v[142:143], 0, s[14:15]
	s_mov_b32 s14, 0x90000
	v_pk_add_f32 v[56:57], v[56:57], v[60:61]
	v_pk_add_f32 v[52:53], v[52:53], v[64:65]
	v_pk_add_f32 v[50:51], v[50:51], v[62:63]
	v_add_co_u32_e32 v60, vcc, s14, v142
	flat_store_dwordx4 v[74:75], v[54:57] offset:512
	flat_store_dwordx4 v[74:75], v[50:53] offset:528
	v_addc_co_u32_e32 v61, vcc, 0, v143, vcc
	flat_load_dwordx4 v[50:53], v[60:61]
	flat_load_dwordx4 v[54:57], v[58:59] offset:16
	s_mov_b64 s[14:15], 0xa0000
	s_waitcnt vmcnt(0) lgkmcnt(0)
	v_pk_add_f32 v[48:49], v[48:49], v[52:53]
	v_pk_add_f32 v[46:47], v[46:47], v[50:51]
	v_pk_add_f32 v[44:45], v[44:45], v[56:57]
	v_pk_add_f32 v[42:43], v[42:43], v[54:55]
	flat_store_dwordx4 v[60:61], v[46:49]
	flat_store_dwordx4 v[58:59], v[42:45] offset:16
	flat_load_dwordx4 v[42:45], v[58:59] offset:512
	s_nop 0
	flat_load_dwordx4 v[46:49], v[58:59] offset:528
	s_waitcnt vmcnt(0) lgkmcnt(0)
	v_pk_add_f32 v[38:39], v[38:39], v[42:43]
	v_lshl_add_u64 v[42:43], v[142:143], 0, s[14:15]
	s_mov_b32 s14, 0xa0000
	v_pk_add_f32 v[40:41], v[40:41], v[44:45]
	v_pk_add_f32 v[36:37], v[36:37], v[48:49]
	v_pk_add_f32 v[34:35], v[34:35], v[46:47]
	v_add_co_u32_e32 v44, vcc, s14, v142
	flat_store_dwordx4 v[58:59], v[38:41] offset:512
	flat_store_dwordx4 v[58:59], v[34:37] offset:528
	v_addc_co_u32_e32 v45, vcc, 0, v143, vcc
	flat_load_dwordx4 v[34:37], v[44:45]
	flat_load_dwordx4 v[38:41], v[42:43] offset:16
	s_mov_b64 s[14:15], 0xb0000
	s_waitcnt vmcnt(0) lgkmcnt(0)
	v_pk_add_f32 v[32:33], v[32:33], v[36:37]
	v_pk_add_f32 v[30:31], v[30:31], v[34:35]
	v_pk_add_f32 v[28:29], v[28:29], v[40:41]
	v_pk_add_f32 v[26:27], v[26:27], v[38:39]
	flat_store_dwordx4 v[44:45], v[30:33]
	flat_store_dwordx4 v[42:43], v[26:29] offset:16
	flat_load_dwordx4 v[26:29], v[42:43] offset:512
	s_nop 0
	flat_load_dwordx4 v[30:33], v[42:43] offset:528
	s_waitcnt vmcnt(0) lgkmcnt(0)
	v_pk_add_f32 v[24:25], v[24:25], v[28:29]
	v_pk_add_f32 v[20:21], v[20:21], v[32:33]
	v_pk_add_f32 v[18:19], v[18:19], v[30:31]
	flat_store_dwordx4 v[42:43], v[18:21] offset:528
	v_pk_add_f32 v[22:23], v[22:23], v[26:27]
	flat_store_dwordx4 v[42:43], v[22:25] offset:512
	v_lshl_add_u64 v[18:19], v[142:143], 0, s[14:15]
	s_mov_b32 s14, 0xb0000
	v_add_co_u32_e32 v28, vcc, s14, v142
	s_mov_b64 s[14:15], -1
	s_nop 0
	v_addc_co_u32_e32 v29, vcc, 0, v143, vcc
	flat_load_dwordx4 v[20:23], v[28:29]
	flat_load_dwordx4 v[24:27], v[18:19] offset:16
	s_and_b64 vcc, exec, s[4:5]
	s_waitcnt vmcnt(0) lgkmcnt(0)
	v_pk_add_f32 v[16:17], v[16:17], v[22:23]
	v_pk_add_f32 v[14:15], v[14:15], v[20:21]
	v_pk_add_f32 v[12:13], v[12:13], v[26:27]
	v_pk_add_f32 v[10:11], v[10:11], v[24:25]
	flat_store_dwordx4 v[28:29], v[14:17]
	flat_store_dwordx4 v[18:19], v[10:13] offset:16
	flat_load_dwordx4 v[10:13], v[18:19] offset:512
	s_nop 0
	flat_load_dwordx4 v[14:17], v[18:19] offset:528
	s_waitcnt vmcnt(0) lgkmcnt(0)
	v_pk_add_f32 v[8:9], v[8:9], v[12:13]
	v_pk_add_f32 v[6:7], v[6:7], v[10:11]
	v_pk_add_f32 v[4:5], v[4:5], v[16:17]
	v_pk_add_f32 v[2:3], v[2:3], v[14:15]
	flat_store_dwordx4 v[18:19], v[6:9] offset:512
	flat_store_dwordx4 v[18:19], v[2:5] offset:528
	s_cbranch_vccnz .LBB0_1226
	s_andn2_b64 vcc, exec, s[2:3]
	s_cbranch_vccnz .LBB0_1225
	s_barrier
	s_branch .LBB0_1225
